# ctx_small proj_resid epilogues (out0, dwn0): 8 residual rows in flight per thread with counted vmcnt, 16-byte stores
# speedup vs baseline: 1.0169x; 1.0067x over previous
.LBB0_771:
	s_mov_b32 s98, 0x3031000
	s_mov_b32 s99, 0
	v_lshl_add_u64 v[54:55], v[4:5], 0, s[98:99]
	v_lshl_add_u64 v[52:53], v[6:7], 0, 0
	s_mov_b32 s98, 0x8000
	global_load_dwordx4 v[12:15], v[52:53], off
	v_lshl_add_u64 v[52:53], v[52:53], 0, s[98:99]
	global_load_dwordx4 v[16:19], v[52:53], off
	v_lshl_add_u64 v[52:53], v[52:53], 0, s[98:99]
	global_load_dwordx4 v[20:23], v[52:53], off
	v_lshl_add_u64 v[52:53], v[52:53], 0, s[98:99]
	global_load_dwordx4 v[24:27], v[52:53], off
	v_lshl_add_u64 v[52:53], v[52:53], 0, s[98:99]
	global_load_dwordx4 v[28:31], v[52:53], off
	v_lshl_add_u64 v[52:53], v[52:53], 0, s[98:99]
	global_load_dwordx4 v[32:35], v[52:53], off
	v_lshl_add_u64 v[52:53], v[52:53], 0, s[98:99]
	global_load_dwordx4 v[36:39], v[52:53], off
	v_lshl_add_u64 v[52:53], v[52:53], 0, s[98:99]
	global_load_dwordx4 v[40:43], v[52:53], off
	v_lshl_add_u64 v[52:53], v[52:53], 0, s[98:99]
	ds_read_b128 v[44:47], v8 offset:0
	ds_read_b128 v[48:51], v8 offset:4224
	s_waitcnt vmcnt(7) lgkmcnt(1)
	v_pk_fma_f32 v[12:13], v[44:45], v[0:1], v[12:13]
	v_pk_fma_f32 v[14:15], v[46:47], v[2:3], v[14:15]
	global_store_dwordx4 v[54:55], v[12:15], off
	v_lshl_add_u64 v[54:55], v[54:55], 0, s[98:99]
	ds_read_b128 v[44:47], v8 offset:8448
	s_waitcnt vmcnt(7) lgkmcnt(1)
	v_pk_fma_f32 v[16:17], v[48:49], v[0:1], v[16:17]
	v_pk_fma_f32 v[18:19], v[50:51], v[2:3], v[18:19]
	global_store_dwordx4 v[54:55], v[16:19], off
	v_lshl_add_u64 v[54:55], v[54:55], 0, s[98:99]
	ds_read_b128 v[48:51], v8 offset:12672
	s_waitcnt vmcnt(7) lgkmcnt(1)
	v_pk_fma_f32 v[20:21], v[44:45], v[0:1], v[20:21]
	v_pk_fma_f32 v[22:23], v[46:47], v[2:3], v[22:23]
	global_store_dwordx4 v[54:55], v[20:23], off
	v_lshl_add_u64 v[54:55], v[54:55], 0, s[98:99]
	ds_read_b128 v[44:47], v8 offset:16896
	s_waitcnt vmcnt(7) lgkmcnt(1)
	v_pk_fma_f32 v[24:25], v[48:49], v[0:1], v[24:25]
	v_pk_fma_f32 v[26:27], v[50:51], v[2:3], v[26:27]
	global_store_dwordx4 v[54:55], v[24:27], off
	v_lshl_add_u64 v[54:55], v[54:55], 0, s[98:99]
	ds_read_b128 v[48:51], v8 offset:21120
	s_waitcnt vmcnt(7) lgkmcnt(1)
	v_pk_fma_f32 v[28:29], v[44:45], v[0:1], v[28:29]
	v_pk_fma_f32 v[30:31], v[46:47], v[2:3], v[30:31]
	global_store_dwordx4 v[54:55], v[28:31], off
	v_lshl_add_u64 v[54:55], v[54:55], 0, s[98:99]
	ds_read_b128 v[44:47], v8 offset:25344
	s_waitcnt vmcnt(7) lgkmcnt(1)
	v_pk_fma_f32 v[32:33], v[48:49], v[0:1], v[32:33]
	v_pk_fma_f32 v[34:35], v[50:51], v[2:3], v[34:35]
	global_store_dwordx4 v[54:55], v[32:35], off
	v_lshl_add_u64 v[54:55], v[54:55], 0, s[98:99]
	ds_read_b128 v[48:51], v8 offset:29568
	s_waitcnt vmcnt(7) lgkmcnt(1)
	v_pk_fma_f32 v[36:37], v[44:45], v[0:1], v[36:37]
	v_pk_fma_f32 v[38:39], v[46:47], v[2:3], v[38:39]
	global_store_dwordx4 v[54:55], v[36:39], off
	v_lshl_add_u64 v[54:55], v[54:55], 0, s[98:99]
	s_waitcnt vmcnt(7) lgkmcnt(0)
	v_pk_fma_f32 v[40:41], v[48:49], v[0:1], v[40:41]
	v_pk_fma_f32 v[42:43], v[50:51], v[2:3], v[42:43]
	global_store_dwordx4 v[54:55], v[40:43], off
	v_lshl_add_u64 v[54:55], v[54:55], 0, s[98:99]
	global_load_dwordx4 v[12:15], v[52:53], off
	v_lshl_add_u64 v[52:53], v[52:53], 0, s[98:99]
	global_load_dwordx4 v[16:19], v[52:53], off
	v_lshl_add_u64 v[52:53], v[52:53], 0, s[98:99]
	global_load_dwordx4 v[20:23], v[52:53], off
	v_lshl_add_u64 v[52:53], v[52:53], 0, s[98:99]
	global_load_dwordx4 v[24:27], v[52:53], off
	v_lshl_add_u64 v[52:53], v[52:53], 0, s[98:99]
	global_load_dwordx4 v[28:31], v[52:53], off
	v_lshl_add_u64 v[52:53], v[52:53], 0, s[98:99]
	global_load_dwordx4 v[32:35], v[52:53], off
	v_lshl_add_u64 v[52:53], v[52:53], 0, s[98:99]
	global_load_dwordx4 v[36:39], v[52:53], off
	v_lshl_add_u64 v[52:53], v[52:53], 0, s[98:99]
	global_load_dwordx4 v[40:43], v[52:53], off
	v_lshl_add_u64 v[52:53], v[52:53], 0, s[98:99]
	ds_read_b128 v[44:47], v8 offset:33792
	ds_read_b128 v[48:51], v8 offset:38016
	s_waitcnt vmcnt(7) lgkmcnt(1)
	v_pk_fma_f32 v[12:13], v[44:45], v[0:1], v[12:13]
	v_pk_fma_f32 v[14:15], v[46:47], v[2:3], v[14:15]
	global_store_dwordx4 v[54:55], v[12:15], off
	v_lshl_add_u64 v[54:55], v[54:55], 0, s[98:99]
	ds_read_b128 v[44:47], v8 offset:42240
	s_waitcnt vmcnt(7) lgkmcnt(1)
	v_pk_fma_f32 v[16:17], v[48:49], v[0:1], v[16:17]
	v_pk_fma_f32 v[18:19], v[50:51], v[2:3], v[18:19]
	global_store_dwordx4 v[54:55], v[16:19], off
	v_lshl_add_u64 v[54:55], v[54:55], 0, s[98:99]
	ds_read_b128 v[48:51], v8 offset:46464
	s_waitcnt vmcnt(7) lgkmcnt(1)
	v_pk_fma_f32 v[20:21], v[44:45], v[0:1], v[20:21]
	v_pk_fma_f32 v[22:23], v[46:47], v[2:3], v[22:23]
	global_store_dwordx4 v[54:55], v[20:23], off
	v_lshl_add_u64 v[54:55], v[54:55], 0, s[98:99]
	ds_read_b128 v[44:47], v8 offset:50688
	s_waitcnt vmcnt(7) lgkmcnt(1)
	v_pk_fma_f32 v[24:25], v[48:49], v[0:1], v[24:25]
	v_pk_fma_f32 v[26:27], v[50:51], v[2:3], v[26:27]
	global_store_dwordx4 v[54:55], v[24:27], off
	v_lshl_add_u64 v[54:55], v[54:55], 0, s[98:99]
	ds_read_b128 v[48:51], v8 offset:54912
	s_waitcnt vmcnt(7) lgkmcnt(1)
	v_pk_fma_f32 v[28:29], v[44:45], v[0:1], v[28:29]
	v_pk_fma_f32 v[30:31], v[46:47], v[2:3], v[30:31]
	global_store_dwordx4 v[54:55], v[28:31], off
	v_lshl_add_u64 v[54:55], v[54:55], 0, s[98:99]
	ds_read_b128 v[44:47], v8 offset:59136
	s_waitcnt vmcnt(7) lgkmcnt(1)
	v_pk_fma_f32 v[32:33], v[48:49], v[0:1], v[32:33]
	v_pk_fma_f32 v[34:35], v[50:51], v[2:3], v[34:35]
	global_store_dwordx4 v[54:55], v[32:35], off
	v_lshl_add_u64 v[54:55], v[54:55], 0, s[98:99]
	ds_read_b128 v[48:51], v8 offset:63360
	s_waitcnt vmcnt(7) lgkmcnt(1)
	v_pk_fma_f32 v[36:37], v[44:45], v[0:1], v[36:37]
	v_pk_fma_f32 v[38:39], v[46:47], v[2:3], v[38:39]
	global_store_dwordx4 v[54:55], v[36:39], off
	v_lshl_add_u64 v[54:55], v[54:55], 0, s[98:99]
	s_waitcnt vmcnt(7) lgkmcnt(0)
	v_pk_fma_f32 v[40:41], v[48:49], v[0:1], v[40:41]
	v_pk_fma_f32 v[42:43], v[50:51], v[2:3], v[42:43]
	global_store_dwordx4 v[54:55], v[40:43], off
	v_lshl_add_u64 v[54:55], v[54:55], 0, s[98:99]
	v_add_u32_e32 v8, 0x10800, v8
	s_mov_b32 s4, 0x80000
	s_mov_b32 s5, 0
	s_add_i32 s17, s17, s22
	s_add_i32 s16, s16, s22
	s_cmp_lt_i32 s17, 64
	s_barrier
	s_cbranch_scc1 .LBB0_761

.LBB0_1219:
	v_mov_b32_e32 v76, v128
	s_mov_b32 s6, 0x12000
	v_and_b32_e32 v78, 15, v76
	v_ashrrev_i32_e32 v77, 8, v76
	v_mul_u32_u24_e32 v78, 0x210, v78
	v_mad_i32_i24 v78, v77, s6, v78
	s_lshl_b32 s6, s8, 8
	v_lshlrev_b32_e32 v79, 1, v76
	s_add_i32 s10, s6, 0xffffc000
	s_lshl_b32 s8, s17, 9
	v_lshlrev_b32_e32 v66, 4, v76
	v_and_b32_e32 v79, 0x180, v79
	v_and_b32_e32 v80, 48, v76
	s_add_u32 s6, s12, s8
	v_and_b32_e32 v66, 0x1f0, v66
	v_add3_u32 v78, v78, v79, v80
	s_addc_u32 s7, s13, 0
	ds_write_b128 v78, v[60:63]
	ds_write_b128 v78, v[56:59] offset:64
	ds_write_b128 v78, v[48:51] offset:8448
	ds_write_b128 v78, v[44:47] offset:8512
	ds_write_b128 v78, v[36:39] offset:16896
	ds_write_b128 v78, v[32:35] offset:16960
	ds_write_b128 v78, v[28:31] offset:25344
	ds_write_b128 v78, v[24:27] offset:25408
	ds_write_b128 v78, v[20:23] offset:33792
	ds_write_b128 v78, v[16:19] offset:33856
	ds_write_b128 v78, v[12:15] offset:42240
	ds_write_b128 v78, v[8:11] offset:42304
	ds_write_b128 v78, v[4:7] offset:50688
	ds_write_b128 v78, v[0:3] offset:50752
	ds_write_b128 v78, v[52:55] offset:59136
	ds_write_b128 v78, v[40:43] offset:59200
	s_waitcnt lgkmcnt(0)
	s_barrier
	global_load_dwordx4 v[0:3], v66, s[6:7]
	v_lshl_add_u32 v8, v77, 7, s10
	v_ashrrev_i32_e32 v9, 31, v8
	v_lshlrev_b64 v[8:9], 12, v[8:9]
	v_lshl_add_u64 v[8:9], s[70:71], 0, v[8:9]
	v_and_b32_e32 v4, 0xff, v76
	v_mul_i32_i24_e32 v6, 0x12000, v77
	v_lshl_add_u64 v[8:9], v[8:9], 0, s[8:9]
	s_mov_b32 s6, 1
	s_mov_b32 s7, 0
	v_mov_b32_e32 v5, v4
	v_or_b32_e32 v6, v6, v66
	v_lshl_add_u64 v[8:9], v[8:9], 0, v[66:67]
	s_mov_b32 s8, 16
	v_lshrrev_b32_e32 v16, 5, v4
	v_lshlrev_b32_e32 v14, 12, v16
	v_mov_b32_e32 v15, 0
	v_lshl_add_u64 v[52:53], v[8:9], 0, v[14:15]
	v_lshl_add_u64 v[54:55], v[8:9], 0, v[14:15]
	v_mad_u32_u24 v56, v16, s14, v6
	s_mov_b32 s98, 0x8000
	s_mov_b32 s99, 0
.LBB0_1220:
	global_load_dwordx4 v[12:15], v[52:53], off
	v_lshl_add_u64 v[52:53], v[52:53], 0, s[98:99]
	global_load_dwordx4 v[16:19], v[52:53], off
	v_lshl_add_u64 v[52:53], v[52:53], 0, s[98:99]
	global_load_dwordx4 v[20:23], v[52:53], off
	v_lshl_add_u64 v[52:53], v[52:53], 0, s[98:99]
	global_load_dwordx4 v[24:27], v[52:53], off
	v_lshl_add_u64 v[52:53], v[52:53], 0, s[98:99]
	global_load_dwordx4 v[28:31], v[52:53], off
	v_lshl_add_u64 v[52:53], v[52:53], 0, s[98:99]
	global_load_dwordx4 v[32:35], v[52:53], off
	v_lshl_add_u64 v[52:53], v[52:53], 0, s[98:99]
	global_load_dwordx4 v[36:39], v[52:53], off
	v_lshl_add_u64 v[52:53], v[52:53], 0, s[98:99]
	global_load_dwordx4 v[40:43], v[52:53], off
	v_lshl_add_u64 v[52:53], v[52:53], 0, s[98:99]
	ds_read_b128 v[44:47], v56 offset:0
	ds_read_b128 v[48:51], v56 offset:4224
	s_waitcnt vmcnt(7) lgkmcnt(1)
	v_pk_fma_f32 v[12:13], v[44:45], v[0:1], v[12:13]
	v_pk_fma_f32 v[14:15], v[46:47], v[2:3], v[14:15]
	global_store_dwordx4 v[54:55], v[12:15], off
	v_lshl_add_u64 v[54:55], v[54:55], 0, s[98:99]
	ds_read_b128 v[44:47], v56 offset:8448
	s_waitcnt vmcnt(7) lgkmcnt(1)
	v_pk_fma_f32 v[16:17], v[48:49], v[0:1], v[16:17]
	v_pk_fma_f32 v[18:19], v[50:51], v[2:3], v[18:19]
	global_store_dwordx4 v[54:55], v[16:19], off
	v_lshl_add_u64 v[54:55], v[54:55], 0, s[98:99]
	ds_read_b128 v[48:51], v56 offset:12672
	s_waitcnt vmcnt(7) lgkmcnt(1)
	v_pk_fma_f32 v[20:21], v[44:45], v[0:1], v[20:21]
	v_pk_fma_f32 v[22:23], v[46:47], v[2:3], v[22:23]
	global_store_dwordx4 v[54:55], v[20:23], off
	v_lshl_add_u64 v[54:55], v[54:55], 0, s[98:99]
	ds_read_b128 v[44:47], v56 offset:16896
	s_waitcnt vmcnt(7) lgkmcnt(1)
	v_pk_fma_f32 v[24:25], v[48:49], v[0:1], v[24:25]
	v_pk_fma_f32 v[26:27], v[50:51], v[2:3], v[26:27]
	global_store_dwordx4 v[54:55], v[24:27], off
	v_lshl_add_u64 v[54:55], v[54:55], 0, s[98:99]
	ds_read_b128 v[48:51], v56 offset:21120
	s_waitcnt vmcnt(7) lgkmcnt(1)
	v_pk_fma_f32 v[28:29], v[44:45], v[0:1], v[28:29]
	v_pk_fma_f32 v[30:31], v[46:47], v[2:3], v[30:31]
	global_store_dwordx4 v[54:55], v[28:31], off
	v_lshl_add_u64 v[54:55], v[54:55], 0, s[98:99]
	ds_read_b128 v[44:47], v56 offset:25344
	s_waitcnt vmcnt(7) lgkmcnt(1)
	v_pk_fma_f32 v[32:33], v[48:49], v[0:1], v[32:33]
	v_pk_fma_f32 v[34:35], v[50:51], v[2:3], v[34:35]
	global_store_dwordx4 v[54:55], v[32:35], off
	v_lshl_add_u64 v[54:55], v[54:55], 0, s[98:99]
	ds_read_b128 v[48:51], v56 offset:29568
	s_waitcnt vmcnt(7) lgkmcnt(1)
	v_pk_fma_f32 v[36:37], v[44:45], v[0:1], v[36:37]
	v_pk_fma_f32 v[38:39], v[46:47], v[2:3], v[38:39]
	global_store_dwordx4 v[54:55], v[36:39], off
	v_lshl_add_u64 v[54:55], v[54:55], 0, s[98:99]
	s_waitcnt vmcnt(7) lgkmcnt(0)
	v_pk_fma_f32 v[40:41], v[48:49], v[0:1], v[40:41]
	v_pk_fma_f32 v[42:43], v[50:51], v[2:3], v[42:43]
	global_store_dwordx4 v[54:55], v[40:43], off
	v_lshl_add_u64 v[54:55], v[54:55], 0, s[98:99]
	global_load_dwordx4 v[12:15], v[52:53], off
	v_lshl_add_u64 v[52:53], v[52:53], 0, s[98:99]
	global_load_dwordx4 v[16:19], v[52:53], off
	v_lshl_add_u64 v[52:53], v[52:53], 0, s[98:99]
	global_load_dwordx4 v[20:23], v[52:53], off
	v_lshl_add_u64 v[52:53], v[52:53], 0, s[98:99]
	global_load_dwordx4 v[24:27], v[52:53], off
	v_lshl_add_u64 v[52:53], v[52:53], 0, s[98:99]
	global_load_dwordx4 v[28:31], v[52:53], off
	v_lshl_add_u64 v[52:53], v[52:53], 0, s[98:99]
	global_load_dwordx4 v[32:35], v[52:53], off
	v_lshl_add_u64 v[52:53], v[52:53], 0, s[98:99]
	global_load_dwordx4 v[36:39], v[52:53], off
	v_lshl_add_u64 v[52:53], v[52:53], 0, s[98:99]
	global_load_dwordx4 v[40:43], v[52:53], off
	v_lshl_add_u64 v[52:53], v[52:53], 0, s[98:99]
	ds_read_b128 v[44:47], v56 offset:33792
	ds_read_b128 v[48:51], v56 offset:38016
	s_waitcnt vmcnt(7) lgkmcnt(1)
	v_pk_fma_f32 v[12:13], v[44:45], v[0:1], v[12:13]
	v_pk_fma_f32 v[14:15], v[46:47], v[2:3], v[14:15]
	global_store_dwordx4 v[54:55], v[12:15], off
	v_lshl_add_u64 v[54:55], v[54:55], 0, s[98:99]
	ds_read_b128 v[44:47], v56 offset:42240
	s_waitcnt vmcnt(7) lgkmcnt(1)
	v_pk_fma_f32 v[16:17], v[48:49], v[0:1], v[16:17]
	v_pk_fma_f32 v[18:19], v[50:51], v[2:3], v[18:19]
	global_store_dwordx4 v[54:55], v[16:19], off
	v_lshl_add_u64 v[54:55], v[54:55], 0, s[98:99]
	ds_read_b128 v[48:51], v56 offset:46464
	s_waitcnt vmcnt(7) lgkmcnt(1)
	v_pk_fma_f32 v[20:21], v[44:45], v[0:1], v[20:21]
	v_pk_fma_f32 v[22:23], v[46:47], v[2:3], v[22:23]
	global_store_dwordx4 v[54:55], v[20:23], off
	v_lshl_add_u64 v[54:55], v[54:55], 0, s[98:99]
	ds_read_b128 v[44:47], v56 offset:50688
	s_waitcnt vmcnt(7) lgkmcnt(1)
	v_pk_fma_f32 v[24:25], v[48:49], v[0:1], v[24:25]
	v_pk_fma_f32 v[26:27], v[50:51], v[2:3], v[26:27]
	global_store_dwordx4 v[54:55], v[24:27], off
	v_lshl_add_u64 v[54:55], v[54:55], 0, s[98:99]
	ds_read_b128 v[48:51], v56 offset:54912
	s_waitcnt vmcnt(7) lgkmcnt(1)
	v_pk_fma_f32 v[28:29], v[44:45], v[0:1], v[28:29]
	v_pk_fma_f32 v[30:31], v[46:47], v[2:3], v[30:31]
	global_store_dwordx4 v[54:55], v[28:31], off
	v_lshl_add_u64 v[54:55], v[54:55], 0, s[98:99]
	ds_read_b128 v[44:47], v56 offset:59136
	s_waitcnt vmcnt(7) lgkmcnt(1)
	v_pk_fma_f32 v[32:33], v[48:49], v[0:1], v[32:33]
	v_pk_fma_f32 v[34:35], v[50:51], v[2:3], v[34:35]
	global_store_dwordx4 v[54:55], v[32:35], off
	v_lshl_add_u64 v[54:55], v[54:55], 0, s[98:99]
	ds_read_b128 v[48:51], v56 offset:63360
	s_waitcnt vmcnt(7) lgkmcnt(1)
	v_pk_fma_f32 v[36:37], v[44:45], v[0:1], v[36:37]
	v_pk_fma_f32 v[38:39], v[46:47], v[2:3], v[38:39]
	global_store_dwordx4 v[54:55], v[36:39], off
	v_lshl_add_u64 v[54:55], v[54:55], 0, s[98:99]
	s_waitcnt vmcnt(7) lgkmcnt(0)
	v_pk_fma_f32 v[40:41], v[48:49], v[0:1], v[40:41]
	v_pk_fma_f32 v[42:43], v[50:51], v[2:3], v[42:43]
	global_store_dwordx4 v[54:55], v[40:43], off
	v_lshl_add_u64 v[54:55], v[54:55], 0, s[98:99]
	s_mov_b32 s8, 0
	s_add_i32 s16, s16, s22
	s_add_i32 s15, s15, s22
	s_cmp_lt_i32 s16, 64
	s_barrier
	s_cbranch_scc1 .LBB0_1210
